# LN epilogues (out-proj, FFN-down): 32 residual loads issued up front with counted vmcnt instead of one round trip each
# speedup vs baseline: 1.0019x; 1.0019x over previous
;     __device__ __forceinline__ void fused(f32x4 (&acc)[2][2][4][2], const Unit& u, int wr, int wc, int fr, int fq, PG8_LAS unsigned char* lds, int wid, int lane) const {
;     ...
;             for (int m = 0; m < 4; ++m) { const size_t off = (size_t)(u.pm * BM + ai * HALF + wr * 64 + m * 16 + fr) * DM + col0;
; #pragma unroll
;                 for (int bj = 0; bj < 2; ++bj)
; #pragma unroll
;                     for (int n = 0; n < 2; ++n) { const size_t o = off + bj * HALF + n * 16; const u32x2v xw = *(const u32x2v*)(XR + o); f32x4 a = acc[ai][bj][m][n];
;                         const f32x4 xv = (f32x4){__uint_as_float(xw.x << 16), __uint_as_float(xw.x & 0xffff0000u), __uint_as_float(xw.y << 16), __uint_as_float(xw.y & 0xffff0000u)};
;                         if (MODE == 1) { const u32x2v pw = *(const u32x2v*)(PP + o); const f32x4 pv = (f32x4){__uint_as_float(pw.x << 16), __uint_as_float(pw.x & 0xffff0000u), __uint_as_float(pw.y << 16), __uint_as_float(pw.y & 0xffff0000u)};
; #pragma unroll
;                             for (int j = 0; j < 4; ++j) a[j] = pv[j] / (1.0f + __expf(-a[j])); }
;                         acc[ai][bj][m][n] = xv * DN_ALPHA + a; }
.LBB0_1684:
	s_lshl_b32 s1, s4, 8
	v_readlane_b32 s2, v255, 12
	s_or_b32 s1, s1, s2
	v_lshrrev_b32_e32 v130, 2, v140
	v_and_or_b32 v134, v130, 12, s1
	s_lshl_b32 s1, s0, 8
	s_add_i32 s2, s1, s37
	v_or_b32_e32 v136, s2, v141
	v_ashrrev_i32_e32 v137, 31, v136
	v_ashrrev_i32_e32 v135, 31, v134
	v_lshlrev_b64 v[130:131], 11, v[136:137]
	v_lshl_add_u64 v[130:131], s[48:49], 0, v[130:131]
	v_lshlrev_b64 v[162:163], 1, v[134:135]
	v_lshl_add_u64 v[130:131], v[130:131], 0, v[162:163]
	s_barrier
	global_load_dwordx2 v[166:167], v[130:131], off
	global_load_dwordx2 v[168:169], v[130:131], off offset:32
	global_load_dwordx2 v[170:171], v[130:131], off offset:256
	global_load_dwordx2 v[172:173], v[130:131], off offset:288
	v_add_co_u32_e32 v130, vcc, 0x8000, v130
	s_nop 1
	v_addc_co_u32_e32 v131, vcc, 0, v131, vcc
	global_load_dwordx2 v[174:175], v[130:131], off
	global_load_dwordx2 v[176:177], v[130:131], off offset:32
	global_load_dwordx2 v[178:179], v[130:131], off offset:256
	global_load_dwordx2 v[180:181], v[130:131], off offset:288
	v_add_co_u32_e32 v130, vcc, 0x8000, v130
	s_nop 1
	v_addc_co_u32_e32 v131, vcc, 0, v131, vcc
	global_load_dwordx2 v[182:183], v[130:131], off
	global_load_dwordx2 v[184:185], v[130:131], off offset:32
	global_load_dwordx2 v[186:187], v[130:131], off offset:256
	global_load_dwordx2 v[188:189], v[130:131], off offset:288
	v_add_co_u32_e32 v130, vcc, 0x8000, v130
	s_nop 1
	v_addc_co_u32_e32 v131, vcc, 0, v131, vcc
	global_load_dwordx2 v[190:191], v[130:131], off
	global_load_dwordx2 v[192:193], v[130:131], off offset:32
	global_load_dwordx2 v[194:195], v[130:131], off offset:256
	global_load_dwordx2 v[196:197], v[130:131], off offset:288
	v_add_co_u32_e32 v130, vcc, 0x28000, v130
	s_nop 1
	v_addc_co_u32_e32 v131, vcc, 0, v131, vcc
	global_load_dwordx2 v[198:199], v[130:131], off
	global_load_dwordx2 v[200:201], v[130:131], off offset:32
	global_load_dwordx2 v[202:203], v[130:131], off offset:256
	global_load_dwordx2 v[204:205], v[130:131], off offset:288
	v_add_co_u32_e32 v130, vcc, 0x8000, v130
	s_nop 1
	v_addc_co_u32_e32 v131, vcc, 0, v131, vcc
	global_load_dwordx2 v[206:207], v[130:131], off
	global_load_dwordx2 v[208:209], v[130:131], off offset:32
	global_load_dwordx2 v[210:211], v[130:131], off offset:256
	global_load_dwordx2 v[212:213], v[130:131], off offset:288
	v_add_co_u32_e32 v130, vcc, 0x8000, v130
	s_nop 1
	v_addc_co_u32_e32 v131, vcc, 0, v131, vcc
	global_load_dwordx2 v[214:215], v[130:131], off
	global_load_dwordx2 v[216:217], v[130:131], off offset:32
	global_load_dwordx2 v[218:219], v[130:131], off offset:256
	global_load_dwordx2 v[154:155], v[130:131], off offset:288
	v_add_co_u32_e32 v130, vcc, 0x8000, v130
	s_nop 1
	v_addc_co_u32_e32 v131, vcc, 0, v131, vcc
	global_load_dwordx2 v[156:157], v[130:131], off
	global_load_dwordx2 v[158:159], v[130:131], off offset:32
	global_load_dwordx2 v[160:161], v[130:131], off offset:256
	global_load_dwordx2 v[152:153], v[130:131], off offset:288
	s_mov_b32 s2, 0x3fb504f3
	v_and_b32_e32 v0, 63, v140
	s_waitcnt vmcnt(31)
	v_lshlrev_b32_e32 v138, 16, v166
	v_and_b32_e32 v139, 0xffff0000, v166
	v_lshlrev_b32_e32 v132, 16, v167
	v_and_b32_e32 v133, 0xffff0000, v167
	v_pk_fma_f32 v[36:37], v[132:133], s[2:3], v[36:37] op_sel_hi:[1,0,1]
	v_pk_fma_f32 v[34:35], v[138:139], s[2:3], v[34:35] op_sel_hi:[1,0,1]
	s_waitcnt vmcnt(30)
	v_lshlrev_b32_e32 v138, 16, v168
	v_and_b32_e32 v139, 0xffff0000, v168
	v_lshlrev_b32_e32 v132, 16, v169
	v_and_b32_e32 v133, 0xffff0000, v169
	v_pk_fma_f32 v[40:41], v[132:133], s[2:3], v[40:41] op_sel_hi:[1,0,1]
	v_pk_fma_f32 v[38:39], v[138:139], s[2:3], v[38:39] op_sel_hi:[1,0,1]
	s_waitcnt vmcnt(29)
	v_lshlrev_b32_e32 v138, 16, v170
	v_and_b32_e32 v139, 0xffff0000, v170
	v_lshlrev_b32_e32 v132, 16, v171
	v_and_b32_e32 v133, 0xffff0000, v171
	v_pk_fma_f32 v[48:49], v[132:133], s[2:3], v[48:49] op_sel_hi:[1,0,1]
	s_waitcnt vmcnt(28)
	v_lshlrev_b32_e32 v132, 16, v172
	v_and_b32_e32 v133, 0xffff0000, v172
	v_lshlrev_b32_e32 v130, 16, v173
	v_and_b32_e32 v131, 0xffff0000, v173
	v_pk_fma_f32 v[60:61], v[130:131], s[2:3], v[60:61] op_sel_hi:[1,0,1]
	v_or_b32_e32 v130, 16, v136
	v_ashrrev_i32_e32 v131, 31, v130
	v_lshlrev_b64 v[130:131], 11, v[130:131]
	v_lshl_add_u64 v[130:131], s[48:49], 0, v[130:131]
	v_pk_fma_f32 v[46:47], v[138:139], s[2:3], v[46:47] op_sel_hi:[1,0,1]
	v_pk_fma_f32 v[58:59], v[132:133], s[2:3], v[58:59] op_sel_hi:[1,0,1]
	v_lshl_add_u64 v[130:131], v[130:131], 0, v[162:163]
	v_add_f32_e32 v143, v48, v49
	v_mov_b32_e32 v142, v59
	s_waitcnt vmcnt(27)
	v_lshlrev_b32_e32 v138, 16, v174
	v_and_b32_e32 v139, 0xffff0000, v174
	v_lshlrev_b32_e32 v132, 16, v175
	v_and_b32_e32 v133, 0xffff0000, v175
	v_pk_fma_f32 v[16:17], v[132:133], s[2:3], v[16:17] op_sel_hi:[1,0,1]
	v_pk_fma_f32 v[14:15], v[138:139], s[2:3], v[14:15] op_sel_hi:[1,0,1]
	s_waitcnt vmcnt(26)
	v_lshlrev_b32_e32 v138, 16, v176
	v_and_b32_e32 v139, 0xffff0000, v176
	v_lshlrev_b32_e32 v132, 16, v177
	v_and_b32_e32 v133, 0xffff0000, v177
	v_pk_fma_f32 v[12:13], v[132:133], s[2:3], v[12:13] op_sel_hi:[1,0,1]
	v_pk_fma_f32 v[10:11], v[138:139], s[2:3], v[10:11] op_sel_hi:[1,0,1]
	s_waitcnt vmcnt(25)
	v_lshlrev_b32_e32 v138, 16, v178
	v_and_b32_e32 v139, 0xffff0000, v178
	v_lshlrev_b32_e32 v132, 16, v179
	v_and_b32_e32 v133, 0xffff0000, v179
	v_pk_fma_f32 v[8:9], v[132:133], s[2:3], v[8:9] op_sel_hi:[1,0,1]
	s_waitcnt vmcnt(24)
;     __device__ __forceinline__ void fused(f32x4 (&acc)[2][2][4][2], const Unit& u, int wr, int wc, int fr, int fq, PG8_LAS unsigned char* lds, int wid, int lane) const {
;     ...
;             for (int m = 0; m < 4; ++m) { const size_t off = (size_t)(u.pm * BM + ai * HALF + wr * 64 + m * 16 + fr) * DM + col0;
; #pragma unroll
;                 for (int bj = 0; bj < 2; ++bj)
; #pragma unroll
;                     for (int n = 0; n < 2; ++n) { const size_t o = off + bj * HALF + n * 16; const u32x2v xw = *(const u32x2v*)(XR + o); f32x4 a = acc[ai][bj][m][n];
;                         const f32x4 xv = (f32x4){__uint_as_float(xw.x << 16), __uint_as_float(xw.x & 0xffff0000u), __uint_as_float(xw.y << 16), __uint_as_float(xw.y & 0xffff0000u)};
;                         if (MODE == 1) { const u32x2v pw = *(const u32x2v*)(PP + o); const f32x4 pv = (f32x4){__uint_as_float(pw.x << 16), __uint_as_float(pw.x & 0xffff0000u), __uint_as_float(pw.y << 16), __uint_as_float(pw.y & 0xffff0000u)};
; #pragma unroll
;                             for (int j = 0; j < 4; ++j) a[j] = pv[j] / (1.0f + __expf(-a[j])); }
;                         acc[ai][bj][m][n] = xv * DN_ALPHA + a; }
	v_lshlrev_b32_e32 v132, 16, v180
	v_and_b32_e32 v133, 0xffff0000, v180
	v_lshlrev_b32_e32 v130, 16, v181
	v_and_b32_e32 v131, 0xffff0000, v181
	v_pk_fma_f32 v[4:5], v[130:131], s[2:3], v[4:5] op_sel_hi:[1,0,1]
	v_or_b32_e32 v130, 32, v136
	v_ashrrev_i32_e32 v131, 31, v130
	v_lshlrev_b64 v[130:131], 11, v[130:131]
	v_pk_fma_f32 v[6:7], v[138:139], s[2:3], v[6:7] op_sel_hi:[1,0,1]
	v_pk_fma_f32 v[2:3], v[132:133], s[2:3], v[2:3] op_sel_hi:[1,0,1]
	v_lshl_add_u64 v[130:131], s[48:49], 0, v[130:131]
	v_lshl_add_u64 v[130:131], v[130:131], 0, v[162:163]
	s_waitcnt vmcnt(23)
	v_lshlrev_b32_e32 v138, 16, v182
	v_and_b32_e32 v139, 0xffff0000, v182
	v_lshlrev_b32_e32 v132, 16, v183
	v_and_b32_e32 v133, 0xffff0000, v183
	v_pk_fma_f32 v[20:21], v[132:133], s[2:3], v[20:21] op_sel_hi:[1,0,1]
	v_pk_fma_f32 v[18:19], v[138:139], s[2:3], v[18:19] op_sel_hi:[1,0,1]
	s_waitcnt vmcnt(22)
	v_lshlrev_b32_e32 v138, 16, v184
	v_and_b32_e32 v139, 0xffff0000, v184
	v_lshlrev_b32_e32 v132, 16, v185
	v_and_b32_e32 v133, 0xffff0000, v185
	v_pk_fma_f32 v[24:25], v[132:133], s[2:3], v[24:25] op_sel_hi:[1,0,1]
	v_pk_fma_f32 v[22:23], v[138:139], s[2:3], v[22:23] op_sel_hi:[1,0,1]
	s_waitcnt vmcnt(21)
	v_lshlrev_b32_e32 v138, 16, v186
	v_and_b32_e32 v139, 0xffff0000, v186
	v_lshlrev_b32_e32 v132, 16, v187
	v_and_b32_e32 v133, 0xffff0000, v187
	v_pk_fma_f32 v[28:29], v[132:133], s[2:3], v[28:29] op_sel_hi:[1,0,1]
	s_waitcnt vmcnt(20)
	v_lshlrev_b32_e32 v132, 16, v188
	v_and_b32_e32 v133, 0xffff0000, v188
	v_lshlrev_b32_e32 v130, 16, v189
	v_and_b32_e32 v131, 0xffff0000, v189
	v_pk_fma_f32 v[32:33], v[130:131], s[2:3], v[32:33] op_sel_hi:[1,0,1]
	v_or_b32_e32 v130, 48, v136
	v_ashrrev_i32_e32 v131, 31, v130
	v_lshlrev_b64 v[130:131], 11, v[130:131]
	v_lshl_add_u64 v[130:131], s[48:49], 0, v[130:131]
	v_pk_fma_f32 v[26:27], v[138:139], s[2:3], v[26:27] op_sel_hi:[1,0,1]
	v_pk_fma_f32 v[30:31], v[132:133], s[2:3], v[30:31] op_sel_hi:[1,0,1]
	v_lshl_add_u64 v[130:131], v[130:131], 0, v[162:163]
	s_waitcnt vmcnt(19)
	v_lshlrev_b32_e32 v138, 16, v190
	v_and_b32_e32 v139, 0xffff0000, v190
	v_lshlrev_b32_e32 v132, 16, v191
	v_and_b32_e32 v133, 0xffff0000, v191
	v_pk_fma_f32 v[44:45], v[132:133], s[2:3], v[44:45] op_sel_hi:[1,0,1]
	v_pk_fma_f32 v[42:43], v[138:139], s[2:3], v[42:43] op_sel_hi:[1,0,1]
	s_waitcnt vmcnt(18)
	v_lshlrev_b32_e32 v138, 16, v192
	v_and_b32_e32 v139, 0xffff0000, v192
	v_lshlrev_b32_e32 v132, 16, v193
	v_and_b32_e32 v133, 0xffff0000, v193
	v_pk_fma_f32 v[52:53], v[132:133], s[2:3], v[52:53] op_sel_hi:[1,0,1]
	v_pk_fma_f32 v[50:51], v[138:139], s[2:3], v[50:51] op_sel_hi:[1,0,1]
	s_waitcnt vmcnt(17)
	v_lshlrev_b32_e32 v138, 16, v194
	v_and_b32_e32 v139, 0xffff0000, v194
	v_lshlrev_b32_e32 v132, 16, v195
	v_and_b32_e32 v133, 0xffff0000, v195
	v_pk_fma_f32 v[56:57], v[132:133], s[2:3], v[56:57] op_sel_hi:[1,0,1]
	s_waitcnt vmcnt(16)
	v_lshlrev_b32_e32 v132, 16, v196
	v_and_b32_e32 v133, 0xffff0000, v196
	v_lshlrev_b32_e32 v130, 16, v197
	v_and_b32_e32 v131, 0xffff0000, v197
	v_pk_fma_f32 v[64:65], v[130:131], s[2:3], v[64:65] op_sel_hi:[1,0,1]
	v_add_u32_e32 v130, 0x80, v136
	v_ashrrev_i32_e32 v131, 31, v130
	v_lshlrev_b64 v[130:131], 11, v[130:131]
	v_pk_fma_f32 v[54:55], v[138:139], s[2:3], v[54:55] op_sel_hi:[1,0,1]
	v_pk_fma_f32 v[62:63], v[132:133], s[2:3], v[62:63] op_sel_hi:[1,0,1]
	v_lshl_add_u64 v[130:131], s[48:49], 0, v[130:131]
	v_lshl_add_u64 v[130:131], v[130:131], 0, v[162:163]
	s_waitcnt vmcnt(15)
	v_lshlrev_b32_e32 v138, 16, v198
	v_and_b32_e32 v139, 0xffff0000, v198
	v_lshlrev_b32_e32 v132, 16, v199
	v_and_b32_e32 v133, 0xffff0000, v199
	v_pk_fma_f32 v[68:69], v[132:133], s[2:3], v[68:69] op_sel_hi:[1,0,1]
	v_pk_fma_f32 v[66:67], v[138:139], s[2:3], v[66:67] op_sel_hi:[1,0,1]
	s_waitcnt vmcnt(14)
	v_lshlrev_b32_e32 v138, 16, v200
	v_and_b32_e32 v139, 0xffff0000, v200
	v_lshlrev_b32_e32 v132, 16, v201
	v_and_b32_e32 v133, 0xffff0000, v201
	v_pk_fma_f32 v[76:77], v[132:133], s[2:3], v[76:77] op_sel_hi:[1,0,1]
	v_pk_fma_f32 v[74:75], v[138:139], s[2:3], v[74:75] op_sel_hi:[1,0,1]
	s_waitcnt vmcnt(13)
	v_lshlrev_b32_e32 v138, 16, v202
	v_and_b32_e32 v139, 0xffff0000, v202
	v_lshlrev_b32_e32 v132, 16, v203
	v_and_b32_e32 v133, 0xffff0000, v203
	v_pk_fma_f32 v[80:81], v[132:133], s[2:3], v[80:81] op_sel_hi:[1,0,1]
	s_waitcnt vmcnt(12)
	v_lshlrev_b32_e32 v132, 16, v204
	v_and_b32_e32 v133, 0xffff0000, v204
	v_lshlrev_b32_e32 v130, 16, v205
	v_and_b32_e32 v131, 0xffff0000, v205
	v_pk_fma_f32 v[88:89], v[130:131], s[2:3], v[88:89] op_sel_hi:[1,0,1]
	v_add_u32_e32 v130, 0x90, v136
	v_ashrrev_i32_e32 v131, 31, v130
	v_lshlrev_b64 v[130:131], 11, v[130:131]
	v_lshl_add_u64 v[130:131], s[48:49], 0, v[130:131]
	v_pk_fma_f32 v[78:79], v[138:139], s[2:3], v[78:79] op_sel_hi:[1,0,1]
	v_pk_fma_f32 v[86:87], v[132:133], s[2:3], v[86:87] op_sel_hi:[1,0,1]
	v_lshl_add_u64 v[130:131], v[130:131], 0, v[162:163]
	s_waitcnt vmcnt(11)
	v_lshlrev_b32_e32 v138, 16, v206
	v_and_b32_e32 v139, 0xffff0000, v206
	v_lshlrev_b32_e32 v132, 16, v207
	v_and_b32_e32 v133, 0xffff0000, v207
	v_pk_fma_f32 v[108:109], v[132:133], s[2:3], v[108:109] op_sel_hi:[1,0,1]
	v_pk_fma_f32 v[106:107], v[138:139], s[2:3], v[106:107] op_sel_hi:[1,0,1]
	s_waitcnt vmcnt(10)
	v_lshlrev_b32_e32 v138, 16, v208
	v_and_b32_e32 v139, 0xffff0000, v208
	v_lshlrev_b32_e32 v132, 16, v209
	v_and_b32_e32 v133, 0xffff0000, v209
	v_pk_fma_f32 v[112:113], v[132:133], s[2:3], v[112:113] op_sel_hi:[1,0,1]
	v_pk_fma_f32 v[110:111], v[138:139], s[2:3], v[110:111] op_sel_hi:[1,0,1]
	s_waitcnt vmcnt(9)
;     __device__ __forceinline__ bool run(const f32x4 (&v)[2][2][4][2], const Unit& u, int wr, int wc, int fr, int fq, PG8_LAS unsigned char* lds, int wid, int lane) const {
;     ...
;                 float s = 0.f;
; #pragma unroll
;                 for (int bj = 0; bj < 2; ++bj)
; #pragma unroll
;                     for (int n = 0; n < 2; ++n) { const f32x4 x = v[ai][bj][m][n]; s += (x[0] + x[1]) + (x[2] + x[3]); }
;                 s += __shfl_xor(s, 16); s += __shfl_xor(s, 32);
;                 const float mw = s * (1.0f / 64.0f); float q = 0.f;
; #pragma unroll
;                 for (int bj = 0; bj < 2; ++bj)
; #pragma unroll
;                     for (int n = 0; n < 2; ++n) { const f32x4 d = v[ai][bj][m][n] - mw; q += (d[0] * d[0] + d[1] * d[1]) + (d[2] * d[2] + d[3] * d[3]); }
;                 q += __shfl_xor(q, 16); q += __shfl_xor(q, 32);
;                 if (fq == 0) P[(ai * HALF + wr * 64 + m * 16 + fr) * 4 + wc] = (f32x2v){mw, q};
;     __device__ __forceinline__ void fused(f32x4 (&acc)[2][2][4][2], const Unit& u, int wr, int wc, int fr, int fq, PG8_LAS unsigned char* lds, int wid, int lane) const {
;     ...
;             for (int m = 0; m < 4; ++m) { const size_t off = (size_t)(u.pm * BM + ai * HALF + wr * 64 + m * 16 + fr) * DM + col0;
; #pragma unroll
;                 for (int bj = 0; bj < 2; ++bj)
; #pragma unroll
;                     for (int n = 0; n < 2; ++n) { const size_t o = off + bj * HALF + n * 16; const u32x2v xw = *(const u32x2v*)(XR + o); f32x4 a = acc[ai][bj][m][n];
;                         const f32x4 xv = (f32x4){__uint_as_float(xw.x << 16), __uint_as_float(xw.x & 0xffff0000u), __uint_as_float(xw.y << 16), __uint_as_float(xw.y & 0xffff0000u)};
;                         if (MODE == 1) { const u32x2v pw = *(const u32x2v*)(PP + o); const f32x4 pv = (f32x4){__uint_as_float(pw.x << 16), __uint_as_float(pw.x & 0xffff0000u), __uint_as_float(pw.y << 16), __uint_as_float(pw.y & 0xffff0000u)};
; #pragma unroll
;                             for (int j = 0; j < 4; ++j) a[j] = pv[j] / (1.0f + __expf(-a[j])); }
;                         acc[ai][bj][m][n] = xv * DN_ALPHA + a; }
;                 asm volatile("" : "+v"(acc[ai][0][m][0]), "+v"(acc[ai][0][m][1]), "+v"(acc[ai][1][m][0]), "+v"(acc[ai][1][m][1]));
;                 if (m & 1) asm volatile("" ::: "memory"); }
	v_lshlrev_b32_e32 v138, 16, v210
	v_and_b32_e32 v139, 0xffff0000, v210
	v_lshlrev_b32_e32 v132, 16, v211
	v_and_b32_e32 v133, 0xffff0000, v211
	v_pk_fma_f32 v[120:121], v[132:133], s[2:3], v[120:121] op_sel_hi:[1,0,1]
	s_waitcnt vmcnt(8)
	v_lshlrev_b32_e32 v132, 16, v212
	v_and_b32_e32 v133, 0xffff0000, v212
	v_lshlrev_b32_e32 v130, 16, v213
	v_and_b32_e32 v131, 0xffff0000, v213
	v_pk_fma_f32 v[124:125], v[130:131], s[2:3], v[124:125] op_sel_hi:[1,0,1]
	v_add_u32_e32 v130, 0xa0, v136
	v_ashrrev_i32_e32 v131, 31, v130
	v_lshlrev_b64 v[130:131], 11, v[130:131]
	v_pk_fma_f32 v[118:119], v[138:139], s[2:3], v[118:119] op_sel_hi:[1,0,1]
	v_pk_fma_f32 v[122:123], v[132:133], s[2:3], v[122:123] op_sel_hi:[1,0,1]
	v_lshl_add_u64 v[130:131], s[48:49], 0, v[130:131]
	v_lshl_add_u64 v[130:131], v[130:131], 0, v[162:163]
	s_waitcnt vmcnt(7)
	v_lshlrev_b32_e32 v138, 16, v214
	v_and_b32_e32 v139, 0xffff0000, v214
	v_lshlrev_b32_e32 v132, 16, v215
	v_and_b32_e32 v133, 0xffff0000, v215
	v_pk_fma_f32 v[128:129], v[132:133], s[2:3], v[128:129] op_sel_hi:[1,0,1]
	v_pk_fma_f32 v[126:127], v[138:139], s[2:3], v[126:127] op_sel_hi:[1,0,1]
	s_waitcnt vmcnt(6)
	v_lshlrev_b32_e32 v138, 16, v216
	v_and_b32_e32 v139, 0xffff0000, v216
	v_lshlrev_b32_e32 v132, 16, v217
	v_and_b32_e32 v133, 0xffff0000, v217
	v_pk_fma_f32 v[116:117], v[132:133], s[2:3], v[116:117] op_sel_hi:[1,0,1]
	v_pk_fma_f32 v[114:115], v[138:139], s[2:3], v[114:115] op_sel_hi:[1,0,1]
	s_waitcnt vmcnt(5)
	v_lshlrev_b32_e32 v138, 16, v218
	v_and_b32_e32 v139, 0xffff0000, v218
	v_lshlrev_b32_e32 v132, 16, v219
	v_and_b32_e32 v133, 0xffff0000, v219
	v_pk_fma_f32 v[102:103], v[138:139], s[2:3], v[102:103] op_sel_hi:[1,0,1]
	s_waitcnt vmcnt(4)
	v_lshlrev_b32_e32 v138, 16, v154
	v_and_b32_e32 v139, 0xffff0000, v154
	v_lshlrev_b32_e32 v130, 16, v155
	v_and_b32_e32 v131, 0xffff0000, v155
	v_pk_fma_f32 v[104:105], v[132:133], s[2:3], v[104:105] op_sel_hi:[1,0,1]
	v_pk_fma_f32 v[132:133], v[130:131], s[2:3], v[92:93] op_sel_hi:[1,0,1]
	v_pk_fma_f32 v[130:131], v[138:139], s[2:3], v[90:91] op_sel_hi:[1,0,1]
	v_add_u32_e32 v90, 0xb0, v136
	v_ashrrev_i32_e32 v91, 31, v90
	v_lshlrev_b64 v[90:91], 11, v[90:91]
	v_lshl_add_u64 v[90:91], s[48:49], 0, v[90:91]
	v_lshl_add_u64 v[136:137], v[90:91], 0, v[162:163]
	s_waitcnt vmcnt(3)
	v_lshlrev_b32_e32 v92, 16, v156
	v_and_b32_e32 v93, 0xffff0000, v156
	v_lshlrev_b32_e32 v90, 16, v157
	v_and_b32_e32 v91, 0xffff0000, v157
	v_pk_fma_f32 v[100:101], v[90:91], s[2:3], v[100:101] op_sel_hi:[1,0,1]
	v_pk_fma_f32 v[98:99], v[92:93], s[2:3], v[98:99] op_sel_hi:[1,0,1]
	s_waitcnt vmcnt(2)
	v_lshlrev_b32_e32 v138, 16, v158
	v_and_b32_e32 v139, 0xffff0000, v158
	v_lshlrev_b32_e32 v90, 16, v159
	v_and_b32_e32 v91, 0xffff0000, v159
	v_pk_fma_f32 v[92:93], v[90:91], s[2:3], v[96:97] op_sel_hi:[1,0,1]
	v_pk_fma_f32 v[90:91], v[138:139], s[2:3], v[94:95] op_sel_hi:[1,0,1]
	v_mov_b32_e32 v138, v38
	v_mov_b32_e32 v139, v41
	s_waitcnt vmcnt(1)
	v_lshlrev_b32_e32 v96, 16, v160
	v_and_b32_e32 v97, 0xffff0000, v160
	v_lshlrev_b32_e32 v94, 16, v161
	v_and_b32_e32 v95, 0xffff0000, v161
	v_pk_fma_f32 v[84:85], v[94:95], s[2:3], v[84:85] op_sel_hi:[1,0,1]
	v_pk_fma_f32 v[82:83], v[96:97], s[2:3], v[82:83] op_sel_hi:[1,0,1]
	v_mov_b32_e32 v136, v34
	v_mov_b32_e32 v137, v37
	s_waitcnt vmcnt(0)
	v_lshlrev_b32_e32 v96, 16, v152
	v_and_b32_e32 v97, 0xffff0000, v152
	v_lshlrev_b32_e32 v94, 16, v153
	v_and_b32_e32 v95, 0xffff0000, v153
	v_pk_fma_f32 v[72:73], v[94:95], s[2:3], v[72:73] op_sel_hi:[1,0,1]
	v_and_b32_e32 v95, 64, v223
	v_xor_b32_e32 v94, 16, v223
	v_add_u32_e32 v95, 64, v95
	v_pk_fma_f32 v[70:71], v[96:97], s[2:3], v[70:71] op_sel_hi:[1,0,1]
	v_cmp_lt_i32_e32 vcc, v94, v95
	v_xor_b32_e32 v96, 32, v223
	v_mov_b32_e32 v97, v36
	v_cndmask_b32_e32 v94, v223, v94, vcc
	v_cmp_lt_i32_e32 vcc, v96, v95
	v_lshlrev_b32_e32 v94, 2, v94
	s_nop 0
	v_cndmask_b32_e32 v95, v223, v96, vcc
	v_mov_b32_e32 v96, v35
	v_pk_add_f32 v[96:97], v[96:97], v[136:137]
	v_mov_b32_e32 v136, v39
	v_mov_b32_e32 v137, v40
	v_pk_add_f32 v[136:137], v[136:137], v[138:139]
	v_add_f32_e32 v96, v96, v97
	v_pk_add_f32 v[136:137], v[136:137], v[136:137] op_sel_hi:[0,1]
	v_add_f32_e32 v97, 0, v96
	v_add_f32_e32 v139, v46, v47
	v_mov_b32_e32 v138, v58
	v_mov_b32_e32 v136, v60
	v_mov_b32_e32 v96, v61
	v_pk_add_f32 v[138:139], v[138:139], v[142:143]
	v_pk_add_f32 v[96:97], v[136:137], v[96:97]
	v_lshlrev_b32_e32 v95, 2, v95
	v_pk_add_f32 v[96:97], v[138:139], v[96:97]
	v_cmp_gt_u32_e32 vcc, 16, v0
	v_add_f32_e32 v96, v96, v97
	ds_bpermute_b32 v97, v94, v96
	s_waitcnt lgkmcnt(0)
	v_add_f32_e32 v96, v96, v97
	ds_bpermute_b32 v97, v95, v96
	s_waitcnt lgkmcnt(0)
	v_add_f32_e32 v97, v96, v97
	v_fmamk_f32 v136, v97, 0xbc800000, v37
	v_fmamk_f32 v138, v97, 0xbc800000, v35
	v_fmamk_f32 v96, v97, 0xbc800000, v36
	v_fmamk_f32 v137, v97, 0xbc800000, v34
	v_mul_f32_e32 v138, v138, v138
	v_mul_f32_e32 v136, v136, v136
	v_fmac_f32_e32 v138, v137, v137
	v_fmac_f32_e32 v136, v96, v96
	v_fmamk_f32 v137, v97, 0xbc800000, v41
	v_fmamk_f32 v139, v97, 0xbc800000, v39
	v_add_f32_e32 v96, v138, v136
	v_fmamk_f32 v136, v97, 0xbc800000, v40
	v_fmamk_f32 v138, v97, 0xbc800000, v38
	v_mul_f32_e32 v139, v139, v139
	v_mul_f32_e32 v137, v137, v137
	v_fmac_f32_e32 v139, v138, v138
	v_fmac_f32_e32 v137, v136, v136
	v_add_f32_e32 v136, v139, v137
	v_fmamk_f32 v137, v97, 0xbc800000, v49
	v_fmamk_f32 v139, v97, 0xbc800000, v47
	v_add_f32_e32 v96, v96, v136
	v_fmamk_f32 v136, v97, 0xbc800000, v48
	v_fmamk_f32 v138, v97, 0xbc800000, v46
	v_mul_f32_e32 v139, v139, v139
	v_mul_f32_e32 v137, v137, v137
	v_fmac_f32_e32 v139, v138, v138
	v_fmac_f32_e32 v137, v136, v136
	v_add_f32_e32 v136, v139, v137
	v_fmamk_f32 v137, v97, 0xbc800000, v61
	v_fmamk_f32 v139, v97, 0xbc800000, v59
	v_add_f32_e32 v96, v136, v96
	v_fmamk_f32 v136, v97, 0xbc800000, v60
	v_fmamk_f32 v138, v97, 0xbc800000, v58
	v_mul_f32_e32 v139, v139, v139
	v_mul_f32_e32 v137, v137, v137
	v_fmac_f32_e32 v139, v138, v138
	v_fmac_f32_e32 v137, v136, v136
	v_add_f32_e32 v136, v139, v137
	v_add_f32_e32 v96, v136, v96
	ds_bpermute_b32 v136, v94, v96
	s_waitcnt lgkmcnt(0)
	v_add_f32_e32 v136, v96, v136
	ds_bpermute_b32 v137, v95, v136
	v_lshl_add_u32 v96, v141, 5, s36
	s_and_saveexec_b64 s[2:3], vcc
	s_cbranch_execz .LBB0_1686
	v_mul_f32_e32 v138, 0x3c800000, v97
	s_waitcnt lgkmcnt(0)
	v_add_f32_e32 v139, v136, v137
	ds_write_b64 v96, v[138:139] offset:1024

;     __device__ __forceinline__ void fused(f32x4 (&acc)[2][2][4][2], const Unit& u, int wr, int wc, int fr, int fq, PG8_LAS unsigned char* lds, int wid, int lane) const {
;     ...
;             for (int m = 0; m < 4; ++m) { const size_t off = (size_t)(u.pm * BM + ai * HALF + wr * 64 + m * 16 + fr) * DM + col0;
; #pragma unroll
;                 for (int bj = 0; bj < 2; ++bj)
; #pragma unroll
;                     for (int n = 0; n < 2; ++n) { const size_t o = off + bj * HALF + n * 16; const u32x2v xw = *(const u32x2v*)(XR + o); f32x4 a = acc[ai][bj][m][n];
;                         const f32x4 xv = (f32x4){__uint_as_float(xw.x << 16), __uint_as_float(xw.x & 0xffff0000u), __uint_as_float(xw.y << 16), __uint_as_float(xw.y & 0xffff0000u)};
;                         if (MODE == 1) { const u32x2v pw = *(const u32x2v*)(PP + o); const f32x4 pv = (f32x4){__uint_as_float(pw.x << 16), __uint_as_float(pw.x & 0xffff0000u), __uint_as_float(pw.y << 16), __uint_as_float(pw.y & 0xffff0000u)};
; #pragma unroll
;                             for (int j = 0; j < 4; ++j) a[j] = pv[j] / (1.0f + __expf(-a[j])); }
;                         acc[ai][bj][m][n] = xv * DN_ALPHA + a; }
.LBB0_2139:
	s_lshl_b32 s1, s6, 8
	v_readlane_b32 s2, v255, 12
	s_or_b32 s1, s1, s2
	v_lshrrev_b32_e32 v130, 2, v140
	v_and_or_b32 v134, v130, 12, s1
	s_lshl_b32 s1, s0, 8
	s_add_i32 s2, s1, s37
	v_or_b32_e32 v136, s2, v141
	v_ashrrev_i32_e32 v137, 31, v136
	v_ashrrev_i32_e32 v135, 31, v134
	v_lshlrev_b64 v[130:131], 11, v[136:137]
	v_lshl_add_u64 v[130:131], s[46:47], 0, v[130:131]
	v_lshlrev_b64 v[162:163], 1, v[134:135]
	v_lshl_add_u64 v[130:131], v[130:131], 0, v[162:163]
	s_barrier
	global_load_dwordx2 v[166:167], v[130:131], off
	global_load_dwordx2 v[168:169], v[130:131], off offset:32
	global_load_dwordx2 v[170:171], v[130:131], off offset:256
	global_load_dwordx2 v[172:173], v[130:131], off offset:288
	v_add_co_u32_e32 v130, vcc, 0x8000, v130
	s_nop 1
	v_addc_co_u32_e32 v131, vcc, 0, v131, vcc
	global_load_dwordx2 v[174:175], v[130:131], off
	global_load_dwordx2 v[176:177], v[130:131], off offset:32
	global_load_dwordx2 v[178:179], v[130:131], off offset:256
	global_load_dwordx2 v[180:181], v[130:131], off offset:288
	v_add_co_u32_e32 v130, vcc, 0x8000, v130
	s_nop 1
	v_addc_co_u32_e32 v131, vcc, 0, v131, vcc
	global_load_dwordx2 v[182:183], v[130:131], off
	global_load_dwordx2 v[184:185], v[130:131], off offset:32
	global_load_dwordx2 v[186:187], v[130:131], off offset:256
	global_load_dwordx2 v[188:189], v[130:131], off offset:288
	v_add_co_u32_e32 v130, vcc, 0x8000, v130
	s_nop 1
	v_addc_co_u32_e32 v131, vcc, 0, v131, vcc
	global_load_dwordx2 v[190:191], v[130:131], off
	global_load_dwordx2 v[192:193], v[130:131], off offset:32
	global_load_dwordx2 v[194:195], v[130:131], off offset:256
	global_load_dwordx2 v[196:197], v[130:131], off offset:288
	v_add_co_u32_e32 v130, vcc, 0x28000, v130
	s_nop 1
	v_addc_co_u32_e32 v131, vcc, 0, v131, vcc
	global_load_dwordx2 v[198:199], v[130:131], off
	global_load_dwordx2 v[200:201], v[130:131], off offset:32
	global_load_dwordx2 v[202:203], v[130:131], off offset:256
	global_load_dwordx2 v[204:205], v[130:131], off offset:288
	v_add_co_u32_e32 v130, vcc, 0x8000, v130
	s_nop 1
	v_addc_co_u32_e32 v131, vcc, 0, v131, vcc
	global_load_dwordx2 v[206:207], v[130:131], off
	global_load_dwordx2 v[208:209], v[130:131], off offset:32
	global_load_dwordx2 v[210:211], v[130:131], off offset:256
	global_load_dwordx2 v[212:213], v[130:131], off offset:288
	v_add_co_u32_e32 v130, vcc, 0x8000, v130
	s_nop 1
	v_addc_co_u32_e32 v131, vcc, 0, v131, vcc
	global_load_dwordx2 v[214:215], v[130:131], off
	global_load_dwordx2 v[216:217], v[130:131], off offset:32
	global_load_dwordx2 v[218:219], v[130:131], off offset:256
	global_load_dwordx2 v[154:155], v[130:131], off offset:288
	v_add_co_u32_e32 v130, vcc, 0x8000, v130
	s_nop 1
	v_addc_co_u32_e32 v131, vcc, 0, v131, vcc
	global_load_dwordx2 v[156:157], v[130:131], off
	global_load_dwordx2 v[158:159], v[130:131], off offset:32
	global_load_dwordx2 v[160:161], v[130:131], off offset:256
	global_load_dwordx2 v[152:153], v[130:131], off offset:288
	s_mov_b32 s2, 0x3fb504f3
	v_and_b32_e32 v0, 63, v140
	s_waitcnt vmcnt(31)
	v_lshlrev_b32_e32 v138, 16, v166
	v_and_b32_e32 v139, 0xffff0000, v166
	v_lshlrev_b32_e32 v132, 16, v167
	v_and_b32_e32 v133, 0xffff0000, v167
	v_pk_fma_f32 v[36:37], v[132:133], s[2:3], v[36:37] op_sel_hi:[1,0,1]
	v_pk_fma_f32 v[34:35], v[138:139], s[2:3], v[34:35] op_sel_hi:[1,0,1]
	s_waitcnt vmcnt(30)
	v_lshlrev_b32_e32 v138, 16, v168
	v_and_b32_e32 v139, 0xffff0000, v168
	v_lshlrev_b32_e32 v132, 16, v169
	v_and_b32_e32 v133, 0xffff0000, v169
	v_pk_fma_f32 v[40:41], v[132:133], s[2:3], v[40:41] op_sel_hi:[1,0,1]
	v_pk_fma_f32 v[38:39], v[138:139], s[2:3], v[38:39] op_sel_hi:[1,0,1]
	s_waitcnt vmcnt(29)
	v_lshlrev_b32_e32 v138, 16, v170
	v_and_b32_e32 v139, 0xffff0000, v170
	v_lshlrev_b32_e32 v132, 16, v171
	v_and_b32_e32 v133, 0xffff0000, v171
	v_pk_fma_f32 v[48:49], v[132:133], s[2:3], v[48:49] op_sel_hi:[1,0,1]
	s_waitcnt vmcnt(28)
	v_lshlrev_b32_e32 v132, 16, v172
	v_and_b32_e32 v133, 0xffff0000, v172
	v_lshlrev_b32_e32 v130, 16, v173
	v_and_b32_e32 v131, 0xffff0000, v173
	v_pk_fma_f32 v[60:61], v[130:131], s[2:3], v[60:61] op_sel_hi:[1,0,1]
	v_or_b32_e32 v130, 16, v136
	v_ashrrev_i32_e32 v131, 31, v130
	v_lshlrev_b64 v[130:131], 11, v[130:131]
	v_lshl_add_u64 v[130:131], s[46:47], 0, v[130:131]
	v_pk_fma_f32 v[46:47], v[138:139], s[2:3], v[46:47] op_sel_hi:[1,0,1]
	v_pk_fma_f32 v[58:59], v[132:133], s[2:3], v[58:59] op_sel_hi:[1,0,1]
	v_lshl_add_u64 v[130:131], v[130:131], 0, v[162:163]
	v_add_f32_e32 v143, v48, v49
	v_mov_b32_e32 v142, v59
	s_waitcnt vmcnt(27)
	v_lshlrev_b32_e32 v138, 16, v174
	v_and_b32_e32 v139, 0xffff0000, v174
	v_lshlrev_b32_e32 v132, 16, v175
	v_and_b32_e32 v133, 0xffff0000, v175
	v_pk_fma_f32 v[16:17], v[132:133], s[2:3], v[16:17] op_sel_hi:[1,0,1]
	v_pk_fma_f32 v[14:15], v[138:139], s[2:3], v[14:15] op_sel_hi:[1,0,1]
	s_waitcnt vmcnt(26)
	v_lshlrev_b32_e32 v138, 16, v176
	v_and_b32_e32 v139, 0xffff0000, v176
	v_lshlrev_b32_e32 v132, 16, v177
	v_and_b32_e32 v133, 0xffff0000, v177
	v_pk_fma_f32 v[12:13], v[132:133], s[2:3], v[12:13] op_sel_hi:[1,0,1]
	v_pk_fma_f32 v[10:11], v[138:139], s[2:3], v[10:11] op_sel_hi:[1,0,1]
	s_waitcnt vmcnt(25)
	v_lshlrev_b32_e32 v138, 16, v178
	v_and_b32_e32 v139, 0xffff0000, v178
	v_lshlrev_b32_e32 v132, 16, v179
	v_and_b32_e32 v133, 0xffff0000, v179
	v_pk_fma_f32 v[8:9], v[132:133], s[2:3], v[8:9] op_sel_hi:[1,0,1]
	s_waitcnt vmcnt(24)
;     __device__ __forceinline__ void fused(f32x4 (&acc)[2][2][4][2], const Unit& u, int wr, int wc, int fr, int fq, PG8_LAS unsigned char* lds, int wid, int lane) const {
;     ...
;             for (int m = 0; m < 4; ++m) { const size_t off = (size_t)(u.pm * BM + ai * HALF + wr * 64 + m * 16 + fr) * DM + col0;
; #pragma unroll
;                 for (int bj = 0; bj < 2; ++bj)
; #pragma unroll
;                     for (int n = 0; n < 2; ++n) { const size_t o = off + bj * HALF + n * 16; const u32x2v xw = *(const u32x2v*)(XR + o); f32x4 a = acc[ai][bj][m][n];
;                         const f32x4 xv = (f32x4){__uint_as_float(xw.x << 16), __uint_as_float(xw.x & 0xffff0000u), __uint_as_float(xw.y << 16), __uint_as_float(xw.y & 0xffff0000u)};
;                         if (MODE == 1) { const u32x2v pw = *(const u32x2v*)(PP + o); const f32x4 pv = (f32x4){__uint_as_float(pw.x << 16), __uint_as_float(pw.x & 0xffff0000u), __uint_as_float(pw.y << 16), __uint_as_float(pw.y & 0xffff0000u)};
; #pragma unroll
;                             for (int j = 0; j < 4; ++j) a[j] = pv[j] / (1.0f + __expf(-a[j])); }
;                         acc[ai][bj][m][n] = xv * DN_ALPHA + a; }
	v_lshlrev_b32_e32 v132, 16, v180
	v_and_b32_e32 v133, 0xffff0000, v180
	v_lshlrev_b32_e32 v130, 16, v181
	v_and_b32_e32 v131, 0xffff0000, v181
	v_pk_fma_f32 v[4:5], v[130:131], s[2:3], v[4:5] op_sel_hi:[1,0,1]
	v_or_b32_e32 v130, 32, v136
	v_ashrrev_i32_e32 v131, 31, v130
	v_lshlrev_b64 v[130:131], 11, v[130:131]
	v_pk_fma_f32 v[6:7], v[138:139], s[2:3], v[6:7] op_sel_hi:[1,0,1]
	v_pk_fma_f32 v[2:3], v[132:133], s[2:3], v[2:3] op_sel_hi:[1,0,1]
	v_lshl_add_u64 v[130:131], s[46:47], 0, v[130:131]
	v_lshl_add_u64 v[130:131], v[130:131], 0, v[162:163]
	s_waitcnt vmcnt(23)
	v_lshlrev_b32_e32 v138, 16, v182
	v_and_b32_e32 v139, 0xffff0000, v182
	v_lshlrev_b32_e32 v132, 16, v183
	v_and_b32_e32 v133, 0xffff0000, v183
	v_pk_fma_f32 v[20:21], v[132:133], s[2:3], v[20:21] op_sel_hi:[1,0,1]
	v_pk_fma_f32 v[18:19], v[138:139], s[2:3], v[18:19] op_sel_hi:[1,0,1]
	s_waitcnt vmcnt(22)
	v_lshlrev_b32_e32 v138, 16, v184
	v_and_b32_e32 v139, 0xffff0000, v184
	v_lshlrev_b32_e32 v132, 16, v185
	v_and_b32_e32 v133, 0xffff0000, v185
	v_pk_fma_f32 v[24:25], v[132:133], s[2:3], v[24:25] op_sel_hi:[1,0,1]
	v_pk_fma_f32 v[22:23], v[138:139], s[2:3], v[22:23] op_sel_hi:[1,0,1]
	s_waitcnt vmcnt(21)
	v_lshlrev_b32_e32 v138, 16, v186
	v_and_b32_e32 v139, 0xffff0000, v186
	v_lshlrev_b32_e32 v132, 16, v187
	v_and_b32_e32 v133, 0xffff0000, v187
	v_pk_fma_f32 v[28:29], v[132:133], s[2:3], v[28:29] op_sel_hi:[1,0,1]
	s_waitcnt vmcnt(20)
	v_lshlrev_b32_e32 v132, 16, v188
	v_and_b32_e32 v133, 0xffff0000, v188
	v_lshlrev_b32_e32 v130, 16, v189
	v_and_b32_e32 v131, 0xffff0000, v189
	v_pk_fma_f32 v[32:33], v[130:131], s[2:3], v[32:33] op_sel_hi:[1,0,1]
	v_or_b32_e32 v130, 48, v136
	v_ashrrev_i32_e32 v131, 31, v130
	v_lshlrev_b64 v[130:131], 11, v[130:131]
	v_lshl_add_u64 v[130:131], s[46:47], 0, v[130:131]
	v_pk_fma_f32 v[26:27], v[138:139], s[2:3], v[26:27] op_sel_hi:[1,0,1]
	v_pk_fma_f32 v[30:31], v[132:133], s[2:3], v[30:31] op_sel_hi:[1,0,1]
	v_lshl_add_u64 v[130:131], v[130:131], 0, v[162:163]
	s_waitcnt vmcnt(19)
	v_lshlrev_b32_e32 v138, 16, v190
	v_and_b32_e32 v139, 0xffff0000, v190
	v_lshlrev_b32_e32 v132, 16, v191
	v_and_b32_e32 v133, 0xffff0000, v191
	v_pk_fma_f32 v[44:45], v[132:133], s[2:3], v[44:45] op_sel_hi:[1,0,1]
	v_pk_fma_f32 v[42:43], v[138:139], s[2:3], v[42:43] op_sel_hi:[1,0,1]
	s_waitcnt vmcnt(18)
	v_lshlrev_b32_e32 v138, 16, v192
	v_and_b32_e32 v139, 0xffff0000, v192
	v_lshlrev_b32_e32 v132, 16, v193
	v_and_b32_e32 v133, 0xffff0000, v193
	v_pk_fma_f32 v[52:53], v[132:133], s[2:3], v[52:53] op_sel_hi:[1,0,1]
	v_pk_fma_f32 v[50:51], v[138:139], s[2:3], v[50:51] op_sel_hi:[1,0,1]
	s_waitcnt vmcnt(17)
	v_lshlrev_b32_e32 v138, 16, v194
	v_and_b32_e32 v139, 0xffff0000, v194
	v_lshlrev_b32_e32 v132, 16, v195
	v_and_b32_e32 v133, 0xffff0000, v195
	v_pk_fma_f32 v[56:57], v[132:133], s[2:3], v[56:57] op_sel_hi:[1,0,1]
	s_waitcnt vmcnt(16)
	v_lshlrev_b32_e32 v132, 16, v196
	v_and_b32_e32 v133, 0xffff0000, v196
	v_lshlrev_b32_e32 v130, 16, v197
	v_and_b32_e32 v131, 0xffff0000, v197
	v_pk_fma_f32 v[64:65], v[130:131], s[2:3], v[64:65] op_sel_hi:[1,0,1]
	v_add_u32_e32 v130, 0x80, v136
	v_ashrrev_i32_e32 v131, 31, v130
	v_lshlrev_b64 v[130:131], 11, v[130:131]
	v_pk_fma_f32 v[54:55], v[138:139], s[2:3], v[54:55] op_sel_hi:[1,0,1]
	v_pk_fma_f32 v[62:63], v[132:133], s[2:3], v[62:63] op_sel_hi:[1,0,1]
	v_lshl_add_u64 v[130:131], s[46:47], 0, v[130:131]
	v_lshl_add_u64 v[130:131], v[130:131], 0, v[162:163]
	s_waitcnt vmcnt(15)
	v_lshlrev_b32_e32 v138, 16, v198
	v_and_b32_e32 v139, 0xffff0000, v198
	v_lshlrev_b32_e32 v132, 16, v199
	v_and_b32_e32 v133, 0xffff0000, v199
	v_pk_fma_f32 v[72:73], v[132:133], s[2:3], v[72:73] op_sel_hi:[1,0,1]
	v_pk_fma_f32 v[70:71], v[138:139], s[2:3], v[70:71] op_sel_hi:[1,0,1]
	s_waitcnt vmcnt(14)
	v_lshlrev_b32_e32 v138, 16, v200
	v_and_b32_e32 v139, 0xffff0000, v200
	v_lshlrev_b32_e32 v132, 16, v201
	v_and_b32_e32 v133, 0xffff0000, v201
	v_pk_fma_f32 v[76:77], v[132:133], s[2:3], v[76:77] op_sel_hi:[1,0,1]
	v_pk_fma_f32 v[74:75], v[138:139], s[2:3], v[74:75] op_sel_hi:[1,0,1]
	s_waitcnt vmcnt(13)
	v_lshlrev_b32_e32 v138, 16, v202
	v_and_b32_e32 v139, 0xffff0000, v202
	v_lshlrev_b32_e32 v132, 16, v203
	v_and_b32_e32 v133, 0xffff0000, v203
	v_pk_fma_f32 v[84:85], v[132:133], s[2:3], v[84:85] op_sel_hi:[1,0,1]
	s_waitcnt vmcnt(12)
	v_lshlrev_b32_e32 v132, 16, v204
	v_and_b32_e32 v133, 0xffff0000, v204
	v_lshlrev_b32_e32 v130, 16, v205
	v_and_b32_e32 v131, 0xffff0000, v205
	v_pk_fma_f32 v[88:89], v[130:131], s[2:3], v[88:89] op_sel_hi:[1,0,1]
	v_add_u32_e32 v130, 0x90, v136
	v_ashrrev_i32_e32 v131, 31, v130
	v_lshlrev_b64 v[130:131], 11, v[130:131]
	v_lshl_add_u64 v[130:131], s[46:47], 0, v[130:131]
	v_pk_fma_f32 v[82:83], v[138:139], s[2:3], v[82:83] op_sel_hi:[1,0,1]
	v_pk_fma_f32 v[86:87], v[132:133], s[2:3], v[86:87] op_sel_hi:[1,0,1]
	v_lshl_add_u64 v[130:131], v[130:131], 0, v[162:163]
	s_waitcnt vmcnt(11)
	v_lshlrev_b32_e32 v138, 16, v206
	v_and_b32_e32 v139, 0xffff0000, v206
	v_lshlrev_b32_e32 v132, 16, v207
	v_and_b32_e32 v133, 0xffff0000, v207
	v_pk_fma_f32 v[108:109], v[132:133], s[2:3], v[108:109] op_sel_hi:[1,0,1]
	v_pk_fma_f32 v[106:107], v[138:139], s[2:3], v[106:107] op_sel_hi:[1,0,1]
	s_waitcnt vmcnt(10)
	v_lshlrev_b32_e32 v138, 16, v208
	v_and_b32_e32 v139, 0xffff0000, v208
	v_lshlrev_b32_e32 v132, 16, v209
	v_and_b32_e32 v133, 0xffff0000, v209
	v_pk_fma_f32 v[116:117], v[132:133], s[2:3], v[116:117] op_sel_hi:[1,0,1]
	v_pk_fma_f32 v[114:115], v[138:139], s[2:3], v[114:115] op_sel_hi:[1,0,1]
	s_waitcnt vmcnt(9)
;     __device__ __forceinline__ bool run(const f32x4 (&v)[2][2][4][2], const Unit& u, int wr, int wc, int fr, int fq, PG8_LAS unsigned char* lds, int wid, int lane) const {
;     ...
;                 float s = 0.f;
; #pragma unroll
;                 for (int bj = 0; bj < 2; ++bj)
; #pragma unroll
;                     for (int n = 0; n < 2; ++n) { const f32x4 x = v[ai][bj][m][n]; s += (x[0] + x[1]) + (x[2] + x[3]); }
;                 s += __shfl_xor(s, 16); s += __shfl_xor(s, 32);
;                 const float mw = s * (1.0f / 64.0f); float q = 0.f;
; #pragma unroll
;                 for (int bj = 0; bj < 2; ++bj)
; #pragma unroll
;                     for (int n = 0; n < 2; ++n) { const f32x4 d = v[ai][bj][m][n] - mw; q += (d[0] * d[0] + d[1] * d[1]) + (d[2] * d[2] + d[3] * d[3]); }
;                 q += __shfl_xor(q, 16); q += __shfl_xor(q, 32);
;                 if (fq == 0) P[(ai * HALF + wr * 64 + m * 16 + fr) * 4 + wc] = (f32x2v){mw, q};
;     __device__ __forceinline__ void fused(f32x4 (&acc)[2][2][4][2], const Unit& u, int wr, int wc, int fr, int fq, PG8_LAS unsigned char* lds, int wid, int lane) const {
;     ...
;             for (int m = 0; m < 4; ++m) { const size_t off = (size_t)(u.pm * BM + ai * HALF + wr * 64 + m * 16 + fr) * DM + col0;
; #pragma unroll
;                 for (int bj = 0; bj < 2; ++bj)
; #pragma unroll
;                     for (int n = 0; n < 2; ++n) { const size_t o = off + bj * HALF + n * 16; const u32x2v xw = *(const u32x2v*)(XR + o); f32x4 a = acc[ai][bj][m][n];
;                         const f32x4 xv = (f32x4){__uint_as_float(xw.x << 16), __uint_as_float(xw.x & 0xffff0000u), __uint_as_float(xw.y << 16), __uint_as_float(xw.y & 0xffff0000u)};
;                         if (MODE == 1) { const u32x2v pw = *(const u32x2v*)(PP + o); const f32x4 pv = (f32x4){__uint_as_float(pw.x << 16), __uint_as_float(pw.x & 0xffff0000u), __uint_as_float(pw.y << 16), __uint_as_float(pw.y & 0xffff0000u)};
; #pragma unroll
;                             for (int j = 0; j < 4; ++j) a[j] = pv[j] / (1.0f + __expf(-a[j])); }
;                         acc[ai][bj][m][n] = xv * DN_ALPHA + a; }
;                 asm volatile("" : "+v"(acc[ai][0][m][0]), "+v"(acc[ai][0][m][1]), "+v"(acc[ai][1][m][0]), "+v"(acc[ai][1][m][1]));
;                 if (m & 1) asm volatile("" ::: "memory"); }
	v_lshlrev_b32_e32 v138, 16, v210
	v_and_b32_e32 v139, 0xffff0000, v210
	v_lshlrev_b32_e32 v132, 16, v211
	v_and_b32_e32 v133, 0xffff0000, v211
	v_pk_fma_f32 v[120:121], v[132:133], s[2:3], v[120:121] op_sel_hi:[1,0,1]
	s_waitcnt vmcnt(8)
	v_lshlrev_b32_e32 v132, 16, v212
	v_and_b32_e32 v133, 0xffff0000, v212
	v_lshlrev_b32_e32 v130, 16, v213
	v_and_b32_e32 v131, 0xffff0000, v213
	v_pk_fma_f32 v[124:125], v[130:131], s[2:3], v[124:125] op_sel_hi:[1,0,1]
	v_add_u32_e32 v130, 0xa0, v136
	v_ashrrev_i32_e32 v131, 31, v130
	v_lshlrev_b64 v[130:131], 11, v[130:131]
	v_pk_fma_f32 v[118:119], v[138:139], s[2:3], v[118:119] op_sel_hi:[1,0,1]
	v_pk_fma_f32 v[122:123], v[132:133], s[2:3], v[122:123] op_sel_hi:[1,0,1]
	v_lshl_add_u64 v[130:131], s[46:47], 0, v[130:131]
	v_lshl_add_u64 v[130:131], v[130:131], 0, v[162:163]
	s_waitcnt vmcnt(7)
	v_lshlrev_b32_e32 v138, 16, v214
	v_and_b32_e32 v139, 0xffff0000, v214
	v_lshlrev_b32_e32 v132, 16, v215
	v_and_b32_e32 v133, 0xffff0000, v215
	v_pk_fma_f32 v[128:129], v[132:133], s[2:3], v[128:129] op_sel_hi:[1,0,1]
	v_pk_fma_f32 v[126:127], v[138:139], s[2:3], v[126:127] op_sel_hi:[1,0,1]
	s_waitcnt vmcnt(6)
	v_lshlrev_b32_e32 v138, 16, v216
	v_and_b32_e32 v139, 0xffff0000, v216
	v_lshlrev_b32_e32 v132, 16, v217
	v_and_b32_e32 v133, 0xffff0000, v217
	v_pk_fma_f32 v[112:113], v[132:133], s[2:3], v[112:113] op_sel_hi:[1,0,1]
	v_pk_fma_f32 v[110:111], v[138:139], s[2:3], v[110:111] op_sel_hi:[1,0,1]
	s_waitcnt vmcnt(5)
	v_lshlrev_b32_e32 v138, 16, v218
	v_and_b32_e32 v139, 0xffff0000, v218
	v_lshlrev_b32_e32 v132, 16, v219
	v_and_b32_e32 v133, 0xffff0000, v219
	v_pk_fma_f32 v[102:103], v[138:139], s[2:3], v[102:103] op_sel_hi:[1,0,1]
	s_waitcnt vmcnt(4)
	v_lshlrev_b32_e32 v138, 16, v154
	v_and_b32_e32 v139, 0xffff0000, v154
	v_lshlrev_b32_e32 v130, 16, v155
	v_and_b32_e32 v131, 0xffff0000, v155
	v_pk_fma_f32 v[104:105], v[132:133], s[2:3], v[104:105] op_sel_hi:[1,0,1]
	v_pk_fma_f32 v[132:133], v[130:131], s[2:3], v[92:93] op_sel_hi:[1,0,1]
	v_pk_fma_f32 v[130:131], v[138:139], s[2:3], v[90:91] op_sel_hi:[1,0,1]
	v_add_u32_e32 v90, 0xb0, v136
	v_ashrrev_i32_e32 v91, 31, v90
	v_lshlrev_b64 v[90:91], 11, v[90:91]
	v_lshl_add_u64 v[90:91], s[46:47], 0, v[90:91]
	v_lshl_add_u64 v[136:137], v[90:91], 0, v[162:163]
	s_waitcnt vmcnt(3)
	v_lshlrev_b32_e32 v92, 16, v156
	v_and_b32_e32 v93, 0xffff0000, v156
	v_lshlrev_b32_e32 v90, 16, v157
	v_and_b32_e32 v91, 0xffff0000, v157
	v_pk_fma_f32 v[100:101], v[90:91], s[2:3], v[100:101] op_sel_hi:[1,0,1]
	v_pk_fma_f32 v[98:99], v[92:93], s[2:3], v[98:99] op_sel_hi:[1,0,1]
	s_waitcnt vmcnt(2)
	v_lshlrev_b32_e32 v138, 16, v158
	v_and_b32_e32 v139, 0xffff0000, v158
	v_lshlrev_b32_e32 v90, 16, v159
	v_and_b32_e32 v91, 0xffff0000, v159
	v_pk_fma_f32 v[92:93], v[90:91], s[2:3], v[96:97] op_sel_hi:[1,0,1]
	v_pk_fma_f32 v[90:91], v[138:139], s[2:3], v[94:95] op_sel_hi:[1,0,1]
	v_mov_b32_e32 v138, v38
	v_mov_b32_e32 v139, v41
	s_waitcnt vmcnt(1)
	v_lshlrev_b32_e32 v96, 16, v160
	v_and_b32_e32 v97, 0xffff0000, v160
	v_lshlrev_b32_e32 v94, 16, v161
	v_and_b32_e32 v95, 0xffff0000, v161
	v_pk_fma_f32 v[80:81], v[94:95], s[2:3], v[80:81] op_sel_hi:[1,0,1]
	v_pk_fma_f32 v[78:79], v[96:97], s[2:3], v[78:79] op_sel_hi:[1,0,1]
	v_mov_b32_e32 v136, v34
	v_mov_b32_e32 v137, v37
	s_waitcnt vmcnt(0)
	v_lshlrev_b32_e32 v96, 16, v152
	v_and_b32_e32 v97, 0xffff0000, v152
	v_lshlrev_b32_e32 v94, 16, v153
	v_and_b32_e32 v95, 0xffff0000, v153
	v_pk_fma_f32 v[68:69], v[94:95], s[2:3], v[68:69] op_sel_hi:[1,0,1]
	v_and_b32_e32 v95, 64, v223
	v_xor_b32_e32 v94, 16, v223
	v_add_u32_e32 v95, 64, v95
	v_pk_fma_f32 v[66:67], v[96:97], s[2:3], v[66:67] op_sel_hi:[1,0,1]
	v_cmp_lt_i32_e32 vcc, v94, v95
	v_xor_b32_e32 v96, 32, v223
	v_mov_b32_e32 v97, v36
	v_cndmask_b32_e32 v94, v223, v94, vcc
	v_cmp_lt_i32_e32 vcc, v96, v95
	v_lshlrev_b32_e32 v94, 2, v94
	s_nop 0
	v_cndmask_b32_e32 v95, v223, v96, vcc
	v_mov_b32_e32 v96, v35
	v_pk_add_f32 v[96:97], v[96:97], v[136:137]
	v_mov_b32_e32 v136, v39
	v_mov_b32_e32 v137, v40
	v_pk_add_f32 v[136:137], v[136:137], v[138:139]
	v_add_f32_e32 v96, v96, v97
	v_pk_add_f32 v[136:137], v[136:137], v[136:137] op_sel_hi:[0,1]
	v_add_f32_e32 v97, 0, v96
	v_add_f32_e32 v139, v46, v47
	v_mov_b32_e32 v138, v58
	v_mov_b32_e32 v136, v60
	v_mov_b32_e32 v96, v61
	v_pk_add_f32 v[138:139], v[138:139], v[142:143]
	v_pk_add_f32 v[96:97], v[136:137], v[96:97]
	v_lshlrev_b32_e32 v95, 2, v95
	v_pk_add_f32 v[96:97], v[138:139], v[96:97]
	v_cmp_gt_u32_e32 vcc, 16, v0
	v_add_f32_e32 v96, v96, v97
	ds_bpermute_b32 v97, v94, v96
	s_waitcnt lgkmcnt(0)
	v_add_f32_e32 v96, v96, v97
	ds_bpermute_b32 v97, v95, v96
	s_waitcnt lgkmcnt(0)
	v_add_f32_e32 v97, v96, v97
	v_fmamk_f32 v136, v97, 0xbc800000, v37
	v_fmamk_f32 v138, v97, 0xbc800000, v35
	v_fmamk_f32 v96, v97, 0xbc800000, v36
	v_fmamk_f32 v137, v97, 0xbc800000, v34
	v_mul_f32_e32 v138, v138, v138
	v_mul_f32_e32 v136, v136, v136
	v_fmac_f32_e32 v138, v137, v137
	v_fmac_f32_e32 v136, v96, v96
	v_fmamk_f32 v137, v97, 0xbc800000, v41
	v_fmamk_f32 v139, v97, 0xbc800000, v39
	v_add_f32_e32 v96, v138, v136
	v_fmamk_f32 v136, v97, 0xbc800000, v40
	v_fmamk_f32 v138, v97, 0xbc800000, v38
	v_mul_f32_e32 v139, v139, v139
	v_mul_f32_e32 v137, v137, v137
	v_fmac_f32_e32 v139, v138, v138
	v_fmac_f32_e32 v137, v136, v136
	v_add_f32_e32 v136, v139, v137
	v_fmamk_f32 v137, v97, 0xbc800000, v49
	v_fmamk_f32 v139, v97, 0xbc800000, v47
	v_add_f32_e32 v96, v96, v136
	v_fmamk_f32 v136, v97, 0xbc800000, v48
	v_fmamk_f32 v138, v97, 0xbc800000, v46
	v_mul_f32_e32 v139, v139, v139
	v_mul_f32_e32 v137, v137, v137
	v_fmac_f32_e32 v139, v138, v138
	v_fmac_f32_e32 v137, v136, v136
	v_add_f32_e32 v136, v139, v137
	v_fmamk_f32 v137, v97, 0xbc800000, v61
	v_fmamk_f32 v139, v97, 0xbc800000, v59
	v_add_f32_e32 v96, v136, v96
	v_fmamk_f32 v136, v97, 0xbc800000, v60
	v_fmamk_f32 v138, v97, 0xbc800000, v58
	v_mul_f32_e32 v139, v139, v139
	v_mul_f32_e32 v137, v137, v137
	v_fmac_f32_e32 v139, v138, v138
	v_fmac_f32_e32 v137, v136, v136
	v_add_f32_e32 v136, v139, v137
	v_add_f32_e32 v96, v136, v96
	ds_bpermute_b32 v136, v94, v96
	s_waitcnt lgkmcnt(0)
	v_add_f32_e32 v136, v96, v136
	ds_bpermute_b32 v137, v95, v136
	v_lshl_add_u32 v96, v141, 5, s36
	s_and_saveexec_b64 s[2:3], vcc
	s_cbranch_execz .LBB0_2141
	v_mul_f32_e32 v138, 0x3c800000, v97
	s_waitcnt lgkmcnt(0)
	v_add_f32_e32 v139, v136, v137
	ds_write_b64 v96, v[138:139] offset:1024
